# NSA selected branch fast bias path: one per-lane select of the bias (mysel ? tc : -inf) per tile, 31 adds straight into the final registers, instead of 31 add+cndmask pairs and 8 vector moves
# speedup vs baseline: 1.0085x; 1.0008x over previous
; __device__ __forceinline__ void nsa_item(const Frame& F, int item, const bf16_t* __restrict__ proj, bf16_t* __restrict__ mix, const float* __restrict__ relb) {
;     ...
;             [&](int, f32x16& p0, f32x16& p1) {
;                 const bool mysel = ((BM[ql * 2 + (jt >> 5)] >> (jt & 31)) & 1u) != 0u;
;                 const int dq = qpos - kb - 4 * hi;
;                 if (qlo - kb >= 190) {
;                     const float tc = tb[127];
; #pragma unroll
;                     for (int r = 0; r < 16; ++r) { p0[r] = mysel ? p0[r] + tc : NEG; p1[r] = mysel ? p1[r] + tc : NEG; }
;                 } else {
.LBB0_834:
	s_andn2_b64 vcc, exec, s[6:7]
	s_cbranch_vccnz .LBB0_836
	ds_read_b32 v133, v208 offset:508
	s_andn2_b64 s[4:5], s[4:5], exec
	s_and_b64 s[6:7], s[44:45], exec
	s_or_b64 s[4:5], s[4:5], s[6:7]
	s_waitcnt lgkmcnt(0)
	s_nop 3
	v_cndmask_b32_e64 v99, v233, v133, s[44:45]
	v_add_f32_e32 v68, v116, v99
	v_add_f32_e32 v69, v117, v99
	v_add_f32_e32 v70, v118, v99
	v_add_f32_e32 v71, v119, v99
	v_add_f32_e32 v72, v120, v99
	v_add_f32_e32 v73, v121, v99
	v_add_f32_e32 v74, v122, v99
	v_add_f32_e32 v75, v123, v99
	v_add_f32_e32 v76, v124, v99
	v_add_f32_e32 v77, v125, v99
	v_add_f32_e32 v78, v126, v99
	v_add_f32_e32 v79, v127, v99
	v_add_f32_e32 v80, v128, v99
	v_add_f32_e32 v81, v129, v99
	v_add_f32_e32 v82, v130, v99
	v_add_f32_e32 v83, v131, v99
	v_add_f32_e32 v84, v100, v99
	v_add_f32_e32 v85, v101, v99
	v_add_f32_e32 v86, v102, v99
	v_add_f32_e32 v87, v103, v99
	v_add_f32_e32 v88, v104, v99
	v_add_f32_e32 v89, v105, v99
	v_add_f32_e32 v90, v106, v99
	v_add_f32_e32 v91, v107, v99
	v_add_f32_e32 v92, v108, v99
	v_add_f32_e32 v93, v109, v99
	v_add_f32_e32 v94, v110, v99
	v_add_f32_e32 v95, v111, v99
	v_add_f32_e32 v96, v112, v99
	v_add_f32_e32 v97, v113, v99
	v_add_f32_e32 v98, v114, v99
	v_mov_b32_e32 v99, v115

; __device__ __forceinline__ void nsa_item(const Frame& F, int item, const bf16_t* __restrict__ proj, bf16_t* __restrict__ mix, const float* __restrict__ relb) {
;     ...
;             [&](int, f32x16& p0, f32x16& p1) {
;                 const bool mysel = ((BM[ql * 2 + (jt >> 5)] >> (jt & 31)) & 1u) != 0u;
;                 const int dq = qpos - kb - 4 * hi;
;                 if (qlo - kb >= 190) {
;                     const float tc = tb[127];
; #pragma unroll
;                     for (int r = 0; r < 16; ++r) { p0[r] = mysel ? p0[r] + tc : NEG; p1[r] = mysel ? p1[r] + tc : NEG; }
;                 } else {
.LBB0_843:
	s_andn2_b64 vcc, exec, s[14:15]
	s_cbranch_vccnz .LBB0_845
	ds_read_b32 v99, v208 offset:508
	s_andn2_b64 s[6:7], s[6:7], exec
	s_and_b64 s[14:15], s[46:47], exec
	s_or_b64 s[6:7], s[6:7], s[14:15]
	s_waitcnt lgkmcnt(0)
	s_nop 2
	v_cndmask_b32_e64 v101, v233, v99, s[46:47]
	v_add_f32_e32 v102, v150, v101
	v_add_f32_e32 v103, v151, v101
	v_add_f32_e32 v104, v152, v101
	v_add_f32_e32 v105, v153, v101
	v_add_f32_e32 v106, v154, v101
	v_add_f32_e32 v107, v155, v101
	v_add_f32_e32 v108, v156, v101
	v_add_f32_e32 v109, v157, v101
	v_add_f32_e32 v110, v158, v101
	v_add_f32_e32 v111, v159, v101
	v_add_f32_e32 v112, v160, v101
	v_add_f32_e32 v113, v161, v101
	v_add_f32_e32 v114, v162, v101
	v_add_f32_e32 v115, v163, v101
	v_add_f32_e32 v116, v164, v101
	v_add_f32_e32 v117, v165, v101
	v_add_f32_e32 v118, v134, v101
	v_add_f32_e32 v119, v135, v101
	v_add_f32_e32 v120, v136, v101
	v_add_f32_e32 v121, v137, v101
	v_add_f32_e32 v122, v138, v101
	v_add_f32_e32 v123, v139, v101
	v_add_f32_e32 v124, v140, v101
	v_add_f32_e32 v125, v141, v101
	v_add_f32_e32 v126, v142, v101
	v_add_f32_e32 v127, v143, v101
	v_add_f32_e32 v128, v144, v101
	v_add_f32_e32 v129, v145, v101
	v_add_f32_e32 v130, v146, v101
	v_add_f32_e32 v131, v147, v101
	v_add_f32_e32 v132, v148, v101
	v_mov_b32_e32 v133, v149
